# residual epilogues (ffn_out, a_out, b_out): counted waits per row block for the first batch of residual loads instead of one vmcnt(0)
# speedup vs baseline: 1.0095x; 1.0003x over previous
.LBB0_162:
	s_lshl_b32 s17, s17, 8
	v_lshl_or_b32 v172, s16, 8, v187
	v_add_u32_e32 v176, s17, v185
	v_ashrrev_i32_e32 v173, 31, v172
	v_lshlrev_b64 v[202:203], 1, v[172:173]
	v_ashrrev_i32_e32 v177, 31, v176
	v_lshl_add_u64 v[174:175], s[22:23], 0, v[202:203]
	v_lshlrev_b64 v[204:205], 11, v[176:177]
	v_lshl_add_u64 v[128:129], v[174:175], 0, v[204:205]
	global_load_dwordx4 v[194:197], v[128:129], off
	global_load_dwordx4 v[198:201], v[128:129], off offset:256
	v_or_b32_e32 v128, 16, v176
	v_or_b32_e32 v130, 32, v176
	v_or_b32_e32 v132, 48, v176
	v_ashrrev_i32_e32 v129, 31, v128
	v_ashrrev_i32_e32 v131, 31, v130
	v_ashrrev_i32_e32 v133, 31, v132
	v_lshlrev_b64 v[182:183], 11, v[128:129]
	v_lshlrev_b64 v[180:181], 11, v[130:131]
	v_lshlrev_b64 v[178:179], 11, v[132:133]
	v_lshl_add_u64 v[128:129], v[174:175], 0, v[182:183]
	v_lshl_add_u64 v[130:131], v[174:175], 0, v[180:181]
	v_lshl_add_u64 v[206:207], v[174:175], 0, v[178:179]
	global_load_dwordx4 v[148:151], v[128:129], off
	global_load_dwordx4 v[144:147], v[128:129], off offset:256
	global_load_dwordx4 v[140:143], v[130:131], off
	global_load_dwordx4 v[136:139], v[130:131], off offset:256
	global_load_dwordx4 v[132:135], v[206:207], off
	s_nop 0
	global_load_dwordx4 v[128:131], v[206:207], off offset:256
	v_and_b32_e32 v206, 64, v159
	v_xor_b32_e32 v193, 16, v159
	v_add_u32_e32 v206, 64, v206
	v_xor_b32_e32 v207, 32, v159
	v_cmp_lt_i32_e32 vcc, v193, v206
	v_lshl_add_u64 v[204:205], s[22:23], 0, v[204:205]
	v_lshl_add_u64 v[202:203], v[204:205], 0, v[202:203]
	v_cndmask_b32_e32 v193, v159, v193, vcc
	v_cmp_lt_i32_e32 vcc, v207, v206
	v_lshlrev_b32_e32 v193, 2, v193
	s_waitcnt vmcnt(7)
	v_lshlrev_b32_e32 v204, 16, v194
	v_and_b32_e32 v205, 0xffff0000, v194
	v_lshlrev_b32_e32 v194, 16, v195
	v_and_b32_e32 v195, 0xffff0000, v195
	v_cndmask_b32_e32 v212, v159, v207, vcc
	v_lshlrev_b32_e32 v206, 16, v196
	v_and_b32_e32 v207, 0xffff0000, v196
	v_lshlrev_b32_e32 v196, 16, v197
	v_and_b32_e32 v197, 0xffff0000, v197
	s_waitcnt vmcnt(6)
	v_lshlrev_b32_e32 v210, 16, v200
	v_and_b32_e32 v211, 0xffff0000, v200
	v_lshlrev_b32_e32 v200, 16, v201
	v_and_b32_e32 v201, 0xffff0000, v201
	v_pk_fma_f32 v[126:127], v[126:127], 0.5, v[194:195] op_sel_hi:[1,0,1]
	v_pk_fma_f32 v[124:125], v[124:125], 0.5, v[204:205] op_sel_hi:[1,0,1]
	v_pk_fma_f32 v[122:123], v[122:123], 0.5, v[196:197] op_sel_hi:[1,0,1]
	v_pk_fma_f32 v[196:197], v[114:115], 0.5, v[200:201] op_sel_hi:[1,0,1]
	v_pk_mul_f32 v[114:115], v[126:127], v[126:127]
	v_pk_fma_f32 v[120:121], v[120:121], 0.5, v[206:207] op_sel_hi:[1,0,1]
	v_pk_fma_f32 v[114:115], v[124:125], v[124:125], v[114:115]
	v_lshlrev_b32_e32 v208, 16, v198
	v_and_b32_e32 v209, 0xffff0000, v198
	v_pk_fma_f32 v[114:115], v[120:121], v[120:121], v[114:115]
	v_lshlrev_b32_e32 v198, 16, v199
	v_and_b32_e32 v199, 0xffff0000, v199
	v_pk_fma_f32 v[116:117], v[116:117], 0.5, v[208:209] op_sel_hi:[1,0,1]
	v_pk_fma_f32 v[114:115], v[122:123], v[122:123], v[114:115]
	v_pk_fma_f32 v[118:119], v[118:119], 0.5, v[198:199] op_sel_hi:[1,0,1]
	v_pk_fma_f32 v[114:115], v[116:117], v[116:117], v[114:115]
	v_pk_fma_f32 v[194:195], v[112:113], 0.5, v[210:211] op_sel_hi:[1,0,1]
	v_pk_fma_f32 v[114:115], v[118:119], v[118:119], v[114:115]
	v_cvt_pk_bf16_f32 v112, v124, v125
	v_cvt_pk_bf16_f32 v113, v126, v127
	s_nop 0
	v_pk_fma_f32 v[114:115], v[194:195], v[194:195], v[114:115]
	s_nop 0
	v_pk_fma_f32 v[114:115], v[196:197], v[196:197], v[114:115]
	s_nop 0
	v_add_f32_e32 v124, v114, v115
	ds_bpermute_b32 v125, v193, v124
	v_cvt_pk_bf16_f32 v114, v120, v121
	v_cvt_pk_bf16_f32 v115, v122, v123
	global_store_dwordx4 v[202:203], v[112:115], off
	v_cvt_pk_bf16_f32 v116, v116, v117
	v_cvt_pk_bf16_f32 v117, v118, v119
	v_cvt_pk_bf16_f32 v118, v194, v195
	v_cvt_pk_bf16_f32 v119, v196, v197
	global_store_dwordx4 v[202:203], v[116:119], off offset:256
	s_waitcnt lgkmcnt(0)
	v_add_f32_e32 v113, v124, v125
	v_lshlrev_b32_e32 v112, 2, v212
	ds_bpermute_b32 v114, v112, v113
	s_and_saveexec_b64 s[54:55], s[8:9]
	s_cbranch_execz .LBB0_164
	s_waitcnt lgkmcnt(0)
	v_add_f32_e32 v113, v113, v114
	ds_write_b32 v188, v113
.LBB0_164:
	s_or_b64 exec, exec, s[54:55]
	s_waitcnt vmcnt(7)
	v_lshlrev_b32_e32 v116, 16, v149
	v_and_b32_e32 v117, 0xffff0000, v149
	s_waitcnt lgkmcnt(0)
	v_lshlrev_b32_e32 v114, 16, v148
	v_and_b32_e32 v115, 0xffff0000, v148
	v_pk_fma_f32 v[110:111], v[110:111], 0.5, v[116:117] op_sel_hi:[1,0,1]
	v_pk_fma_f32 v[114:115], v[108:109], 0.5, v[114:115] op_sel_hi:[1,0,1]
	v_pk_mul_f32 v[116:117], v[110:111], v[110:111]
	v_cvt_pk_bf16_f32 v108, v114, v115
	v_cvt_pk_bf16_f32 v109, v110, v111
	v_lshlrev_b32_e32 v110, 16, v150
	v_and_b32_e32 v111, 0xffff0000, v150
	v_pk_fma_f32 v[114:115], v[114:115], v[114:115], v[116:117]
	v_pk_fma_f32 v[104:105], v[104:105], 0.5, v[110:111] op_sel_hi:[1,0,1]
	s_nop 0
	v_pk_fma_f32 v[114:115], v[104:105], v[104:105], v[114:115]
	v_cvt_pk_bf16_f32 v110, v104, v105
	v_lshlrev_b32_e32 v104, 16, v151
	v_and_b32_e32 v105, 0xffff0000, v151
	v_pk_fma_f32 v[104:105], v[106:107], 0.5, v[104:105] op_sel_hi:[1,0,1]
	s_nop 0
	v_pk_fma_f32 v[106:107], v[104:105], v[104:105], v[114:115]
	v_cvt_pk_bf16_f32 v111, v104, v105
	s_waitcnt vmcnt(6)
	v_lshlrev_b32_e32 v104, 16, v144
	v_and_b32_e32 v105, 0xffff0000, v144
	v_pk_fma_f32 v[100:101], v[100:101], 0.5, v[104:105] op_sel_hi:[1,0,1]
	s_nop 0
	v_pk_fma_f32 v[104:105], v[100:101], v[100:101], v[106:107]
	v_lshlrev_b32_e32 v106, 16, v145
	v_and_b32_e32 v107, 0xffff0000, v145
	v_pk_fma_f32 v[102:103], v[102:103], 0.5, v[106:107] op_sel_hi:[1,0,1]
	v_lshlrev_b32_e32 v106, 16, v146
	v_and_b32_e32 v107, 0xffff0000, v146
	v_pk_fma_f32 v[104:105], v[102:103], v[102:103], v[104:105]
	v_pk_fma_f32 v[106:107], v[96:97], 0.5, v[106:107] op_sel_hi:[1,0,1]
	s_nop 0
	v_pk_fma_f32 v[96:97], v[106:107], v[106:107], v[104:105]
	v_lshlrev_b32_e32 v104, 16, v147
	v_and_b32_e32 v105, 0xffff0000, v147
	v_pk_fma_f32 v[104:105], v[98:99], 0.5, v[104:105] op_sel_hi:[1,0,1]
	s_nop 0
	v_pk_fma_f32 v[96:97], v[104:105], v[104:105], v[96:97]
	s_nop 0
	v_add_f32_e32 v99, v96, v97
	ds_bpermute_b32 v113, v193, v99
	v_lshl_add_u64 v[96:97], s[22:23], 0, v[182:183]
	v_lshl_add_u64 v[114:115], v[172:173], 1, v[96:97]
	global_store_dwordx4 v[114:115], v[108:111], off
	v_cvt_pk_bf16_f32 v98, v100, v101
	s_waitcnt lgkmcnt(0)
	v_add_f32_e32 v96, v99, v113
	ds_bpermute_b32 v97, v112, v96
	v_cvt_pk_bf16_f32 v99, v102, v103
	v_cvt_pk_bf16_f32 v100, v106, v107
	v_cvt_pk_bf16_f32 v101, v104, v105
	global_store_dwordx4 v[114:115], v[98:101], off offset:256
	s_and_saveexec_b64 s[54:55], s[8:9]
	s_cbranch_execz .LBB0_166
	s_waitcnt lgkmcnt(0)
	v_add_f32_e32 v96, v96, v97
	ds_write_b32 v188, v96 offset:256
.LBB0_166:
	s_or_b64 exec, exec, s[54:55]
	s_waitcnt vmcnt(7)
	v_lshlrev_b32_e32 v98, 16, v141
	v_and_b32_e32 v99, 0xffff0000, v141
	v_lshlrev_b32_e32 v96, 16, v140
	s_waitcnt lgkmcnt(0)
	v_and_b32_e32 v97, 0xffff0000, v140
	v_pk_fma_f32 v[94:95], v[94:95], 0.5, v[98:99] op_sel_hi:[1,0,1]
	v_pk_fma_f32 v[96:97], v[92:93], 0.5, v[96:97] op_sel_hi:[1,0,1]
	v_pk_mul_f32 v[98:99], v[94:95], v[94:95]
	v_cvt_pk_bf16_f32 v92, v96, v97
	v_cvt_pk_bf16_f32 v93, v94, v95
	v_lshlrev_b32_e32 v94, 16, v142
	v_and_b32_e32 v95, 0xffff0000, v142
	v_pk_fma_f32 v[96:97], v[96:97], v[96:97], v[98:99]
	v_pk_fma_f32 v[88:89], v[88:89], 0.5, v[94:95] op_sel_hi:[1,0,1]
	s_nop 0
	v_pk_fma_f32 v[96:97], v[88:89], v[88:89], v[96:97]
	v_cvt_pk_bf16_f32 v94, v88, v89
	v_lshlrev_b32_e32 v88, 16, v143
	v_and_b32_e32 v89, 0xffff0000, v143
	v_pk_fma_f32 v[88:89], v[90:91], 0.5, v[88:89] op_sel_hi:[1,0,1]
	s_nop 0
	v_pk_fma_f32 v[90:91], v[88:89], v[88:89], v[96:97]
	v_cvt_pk_bf16_f32 v95, v88, v89
	s_waitcnt vmcnt(6)
	v_lshlrev_b32_e32 v88, 16, v136
	v_and_b32_e32 v89, 0xffff0000, v136
	v_pk_fma_f32 v[84:85], v[84:85], 0.5, v[88:89] op_sel_hi:[1,0,1]
	s_nop 0
	v_pk_fma_f32 v[88:89], v[84:85], v[84:85], v[90:91]
	v_lshlrev_b32_e32 v90, 16, v137
	v_and_b32_e32 v91, 0xffff0000, v137
	v_pk_fma_f32 v[86:87], v[86:87], 0.5, v[90:91] op_sel_hi:[1,0,1]
	v_lshlrev_b32_e32 v90, 16, v138
	v_and_b32_e32 v91, 0xffff0000, v138
	v_pk_fma_f32 v[88:89], v[86:87], v[86:87], v[88:89]
	v_pk_fma_f32 v[90:91], v[80:81], 0.5, v[90:91] op_sel_hi:[1,0,1]
	s_nop 0
	v_pk_fma_f32 v[80:81], v[90:91], v[90:91], v[88:89]
	v_lshlrev_b32_e32 v88, 16, v139
	v_and_b32_e32 v89, 0xffff0000, v139
	v_pk_fma_f32 v[88:89], v[82:83], 0.5, v[88:89] op_sel_hi:[1,0,1]
	s_nop 0
	v_pk_fma_f32 v[80:81], v[88:89], v[88:89], v[80:81]
	s_nop 0
	v_add_f32_e32 v83, v80, v81
	ds_bpermute_b32 v98, v193, v83
	v_lshl_add_u64 v[80:81], s[22:23], 0, v[180:181]
	v_lshl_add_u64 v[96:97], v[172:173], 1, v[80:81]
	global_store_dwordx4 v[96:97], v[92:95], off
	v_cvt_pk_bf16_f32 v82, v84, v85
	s_waitcnt lgkmcnt(0)
	v_add_f32_e32 v80, v83, v98
	ds_bpermute_b32 v81, v112, v80
	v_cvt_pk_bf16_f32 v83, v86, v87
	v_cvt_pk_bf16_f32 v84, v90, v91
	v_cvt_pk_bf16_f32 v85, v88, v89
	global_store_dwordx4 v[96:97], v[82:85], off offset:256
	s_and_saveexec_b64 s[54:55], s[8:9]
	s_cbranch_execz .LBB0_168
	s_waitcnt lgkmcnt(0)
	v_add_f32_e32 v80, v80, v81
	ds_write_b32 v188, v80 offset:512
.LBB0_168:
	s_or_b64 exec, exec, s[54:55]
	s_waitcnt vmcnt(7)
	v_lshlrev_b32_e32 v82, 16, v133
	v_and_b32_e32 v83, 0xffff0000, v133
	v_lshlrev_b32_e32 v80, 16, v132
	s_waitcnt lgkmcnt(0)
	v_and_b32_e32 v81, 0xffff0000, v132
	v_pk_fma_f32 v[78:79], v[78:79], 0.5, v[82:83] op_sel_hi:[1,0,1]
	v_pk_fma_f32 v[80:81], v[76:77], 0.5, v[80:81] op_sel_hi:[1,0,1]
	v_pk_mul_f32 v[82:83], v[78:79], v[78:79]
	v_cvt_pk_bf16_f32 v76, v80, v81
	v_cvt_pk_bf16_f32 v77, v78, v79
	v_lshlrev_b32_e32 v78, 16, v134
	v_and_b32_e32 v79, 0xffff0000, v134
	v_pk_fma_f32 v[80:81], v[80:81], v[80:81], v[82:83]
	v_pk_fma_f32 v[72:73], v[72:73], 0.5, v[78:79] op_sel_hi:[1,0,1]
	s_nop 0
	v_pk_fma_f32 v[80:81], v[72:73], v[72:73], v[80:81]
	v_cvt_pk_bf16_f32 v78, v72, v73
	v_lshlrev_b32_e32 v72, 16, v135
	v_and_b32_e32 v73, 0xffff0000, v135
	v_pk_fma_f32 v[72:73], v[74:75], 0.5, v[72:73] op_sel_hi:[1,0,1]
	s_nop 0
	v_pk_fma_f32 v[74:75], v[72:73], v[72:73], v[80:81]
	v_cvt_pk_bf16_f32 v79, v72, v73
	s_waitcnt vmcnt(6)
	v_lshlrev_b32_e32 v72, 16, v128
	v_and_b32_e32 v73, 0xffff0000, v128
	v_pk_fma_f32 v[68:69], v[68:69], 0.5, v[72:73] op_sel_hi:[1,0,1]
	s_nop 0
	v_pk_fma_f32 v[72:73], v[68:69], v[68:69], v[74:75]
	v_lshlrev_b32_e32 v74, 16, v129
	v_and_b32_e32 v75, 0xffff0000, v129
	v_pk_fma_f32 v[70:71], v[70:71], 0.5, v[74:75] op_sel_hi:[1,0,1]
	v_lshlrev_b32_e32 v74, 16, v130
	v_and_b32_e32 v75, 0xffff0000, v130
	v_pk_fma_f32 v[72:73], v[70:71], v[70:71], v[72:73]
	v_pk_fma_f32 v[74:75], v[64:65], 0.5, v[74:75] op_sel_hi:[1,0,1]
	s_nop 0
	v_pk_fma_f32 v[64:65], v[74:75], v[74:75], v[72:73]
	v_lshlrev_b32_e32 v72, 16, v131
	v_and_b32_e32 v73, 0xffff0000, v131
	v_pk_fma_f32 v[72:73], v[66:67], 0.5, v[72:73] op_sel_hi:[1,0,1]
	s_nop 0
	v_pk_fma_f32 v[64:65], v[72:73], v[72:73], v[64:65]
	s_nop 0
	v_add_f32_e32 v67, v64, v65
	ds_bpermute_b32 v82, v193, v67
	v_lshl_add_u64 v[64:65], s[22:23], 0, v[178:179]
	v_lshl_add_u64 v[80:81], v[172:173], 1, v[64:65]
	global_store_dwordx4 v[80:81], v[76:79], off
	v_cvt_pk_bf16_f32 v66, v68, v69
	s_waitcnt lgkmcnt(0)
	v_add_f32_e32 v64, v67, v82
	ds_bpermute_b32 v65, v112, v64
	v_cvt_pk_bf16_f32 v67, v70, v71
	v_cvt_pk_bf16_f32 v68, v74, v75
	v_cvt_pk_bf16_f32 v69, v72, v73
	global_store_dwordx4 v[80:81], v[66:69], off offset:256
	s_and_saveexec_b64 s[54:55], s[8:9]
	s_cbranch_execz .LBB0_170
	s_waitcnt lgkmcnt(0)
	v_add_f32_e32 v64, v64, v65
	ds_write_b32 v188, v64 offset:768

.LBB0_443:
	s_lshl_b32 s15, s58, 8
	v_lshl_or_b32 v172, s14, 8, v187
	v_add_u32_e32 v176, s15, v185
	v_ashrrev_i32_e32 v173, 31, v172
	v_lshlrev_b64 v[202:203], 1, v[172:173]
	v_ashrrev_i32_e32 v177, 31, v176
	v_lshl_add_u64 v[174:175], s[20:21], 0, v[202:203]
	v_lshlrev_b64 v[204:205], 11, v[176:177]
	v_lshl_add_u64 v[128:129], v[174:175], 0, v[204:205]
	global_load_dwordx4 v[194:197], v[128:129], off
	global_load_dwordx4 v[198:201], v[128:129], off offset:256
	v_or_b32_e32 v128, 16, v176
	v_or_b32_e32 v130, 32, v176
	v_or_b32_e32 v132, 48, v176
	v_ashrrev_i32_e32 v129, 31, v128
	v_ashrrev_i32_e32 v131, 31, v130
	v_ashrrev_i32_e32 v133, 31, v132
	v_lshlrev_b64 v[182:183], 11, v[128:129]
	v_lshlrev_b64 v[180:181], 11, v[130:131]
	v_lshlrev_b64 v[178:179], 11, v[132:133]
	v_lshl_add_u64 v[128:129], v[174:175], 0, v[182:183]
	v_lshl_add_u64 v[130:131], v[174:175], 0, v[180:181]
	v_lshl_add_u64 v[206:207], v[174:175], 0, v[178:179]
	global_load_dwordx4 v[148:151], v[128:129], off
	global_load_dwordx4 v[144:147], v[128:129], off offset:256
	global_load_dwordx4 v[140:143], v[130:131], off
	global_load_dwordx4 v[136:139], v[130:131], off offset:256
	global_load_dwordx4 v[132:135], v[206:207], off
	s_nop 0
	global_load_dwordx4 v[128:131], v[206:207], off offset:256
	v_and_b32_e32 v206, 64, v159
	v_xor_b32_e32 v193, 16, v159
	v_add_u32_e32 v206, 64, v206
	v_xor_b32_e32 v207, 32, v159
	v_cmp_lt_i32_e32 vcc, v193, v206
	v_lshl_add_u64 v[204:205], s[20:21], 0, v[204:205]
	v_lshl_add_u64 v[202:203], v[204:205], 0, v[202:203]
	v_cndmask_b32_e32 v193, v159, v193, vcc
	v_cmp_lt_i32_e32 vcc, v207, v206
	v_lshlrev_b32_e32 v193, 2, v193
	s_waitcnt vmcnt(7)
	v_lshlrev_b32_e32 v204, 16, v194
	v_and_b32_e32 v205, 0xffff0000, v194
	v_lshlrev_b32_e32 v194, 16, v195
	v_and_b32_e32 v195, 0xffff0000, v195
	v_cndmask_b32_e32 v212, v159, v207, vcc
	v_lshlrev_b32_e32 v206, 16, v196
	v_and_b32_e32 v207, 0xffff0000, v196
	v_lshlrev_b32_e32 v196, 16, v197
	v_and_b32_e32 v197, 0xffff0000, v197
	s_waitcnt vmcnt(6)
	v_lshlrev_b32_e32 v210, 16, v200
	v_and_b32_e32 v211, 0xffff0000, v200
	v_lshlrev_b32_e32 v200, 16, v201
	v_and_b32_e32 v201, 0xffff0000, v201
	v_pk_add_f32 v[126:127], v[126:127], v[194:195]
	v_pk_add_f32 v[124:125], v[124:125], v[204:205]
	v_pk_add_f32 v[122:123], v[122:123], v[196:197]
	v_pk_add_f32 v[196:197], v[114:115], v[200:201]
	v_pk_mul_f32 v[114:115], v[126:127], v[126:127]
	v_pk_add_f32 v[120:121], v[120:121], v[206:207]
	v_pk_fma_f32 v[114:115], v[124:125], v[124:125], v[114:115]
	v_lshlrev_b32_e32 v208, 16, v198
	v_and_b32_e32 v209, 0xffff0000, v198
	v_pk_fma_f32 v[114:115], v[120:121], v[120:121], v[114:115]
	v_lshlrev_b32_e32 v198, 16, v199
	v_and_b32_e32 v199, 0xffff0000, v199
	v_pk_add_f32 v[116:117], v[116:117], v[208:209]
	v_pk_fma_f32 v[114:115], v[122:123], v[122:123], v[114:115]
	v_pk_add_f32 v[118:119], v[118:119], v[198:199]
	v_pk_fma_f32 v[114:115], v[116:117], v[116:117], v[114:115]
	v_pk_add_f32 v[194:195], v[112:113], v[210:211]
	v_pk_fma_f32 v[114:115], v[118:119], v[118:119], v[114:115]
	v_cvt_pk_bf16_f32 v112, v124, v125
	v_cvt_pk_bf16_f32 v113, v126, v127
	s_nop 0
	v_pk_fma_f32 v[114:115], v[194:195], v[194:195], v[114:115]
	s_nop 0
	v_pk_fma_f32 v[114:115], v[196:197], v[196:197], v[114:115]
	s_nop 0
	v_add_f32_e32 v124, v114, v115
	ds_bpermute_b32 v125, v193, v124
	v_cvt_pk_bf16_f32 v114, v120, v121
	v_cvt_pk_bf16_f32 v115, v122, v123
	global_store_dwordx4 v[202:203], v[112:115], off
	v_cvt_pk_bf16_f32 v116, v116, v117
	v_cvt_pk_bf16_f32 v117, v118, v119
	v_cvt_pk_bf16_f32 v118, v194, v195
	v_cvt_pk_bf16_f32 v119, v196, v197
	global_store_dwordx4 v[202:203], v[116:119], off offset:256
	s_waitcnt lgkmcnt(0)
	v_add_f32_e32 v113, v124, v125
	v_lshlrev_b32_e32 v112, 2, v212
	ds_bpermute_b32 v114, v112, v113
	s_and_saveexec_b64 s[58:59], s[8:9]
	s_cbranch_execz .LBB0_445
	s_waitcnt lgkmcnt(0)
	v_add_f32_e32 v113, v113, v114
	ds_write_b32 v188, v113
.LBB0_445:
	s_or_b64 exec, exec, s[58:59]
	s_waitcnt vmcnt(7)
	v_lshlrev_b32_e32 v116, 16, v149
	v_and_b32_e32 v117, 0xffff0000, v149
	s_waitcnt lgkmcnt(0)
	v_lshlrev_b32_e32 v114, 16, v148
	v_and_b32_e32 v115, 0xffff0000, v148
	v_pk_add_f32 v[110:111], v[110:111], v[116:117]
	v_pk_add_f32 v[114:115], v[108:109], v[114:115]
	v_pk_mul_f32 v[116:117], v[110:111], v[110:111]
	v_cvt_pk_bf16_f32 v108, v114, v115
	v_cvt_pk_bf16_f32 v109, v110, v111
	v_lshlrev_b32_e32 v110, 16, v150
	v_and_b32_e32 v111, 0xffff0000, v150
	v_pk_fma_f32 v[114:115], v[114:115], v[114:115], v[116:117]
	v_pk_add_f32 v[104:105], v[104:105], v[110:111]
	s_nop 0
	v_pk_fma_f32 v[114:115], v[104:105], v[104:105], v[114:115]
	v_cvt_pk_bf16_f32 v110, v104, v105
	v_lshlrev_b32_e32 v104, 16, v151
	v_and_b32_e32 v105, 0xffff0000, v151
	v_pk_add_f32 v[104:105], v[106:107], v[104:105]
	s_nop 0
	v_pk_fma_f32 v[106:107], v[104:105], v[104:105], v[114:115]
	v_cvt_pk_bf16_f32 v111, v104, v105
	s_waitcnt vmcnt(6)
	v_lshlrev_b32_e32 v104, 16, v144
	v_and_b32_e32 v105, 0xffff0000, v144
	v_pk_add_f32 v[100:101], v[100:101], v[104:105]
	s_nop 0
	v_pk_fma_f32 v[104:105], v[100:101], v[100:101], v[106:107]
	v_lshlrev_b32_e32 v106, 16, v145
	v_and_b32_e32 v107, 0xffff0000, v145
	v_pk_add_f32 v[102:103], v[102:103], v[106:107]
	v_lshlrev_b32_e32 v106, 16, v146
	v_and_b32_e32 v107, 0xffff0000, v146
	v_pk_fma_f32 v[104:105], v[102:103], v[102:103], v[104:105]
	v_pk_add_f32 v[106:107], v[96:97], v[106:107]
	s_nop 0
	v_pk_fma_f32 v[96:97], v[106:107], v[106:107], v[104:105]
	v_lshlrev_b32_e32 v104, 16, v147
	v_and_b32_e32 v105, 0xffff0000, v147
	v_pk_add_f32 v[104:105], v[98:99], v[104:105]
	s_nop 0
	v_pk_fma_f32 v[96:97], v[104:105], v[104:105], v[96:97]
	s_nop 0
	v_add_f32_e32 v99, v96, v97
	ds_bpermute_b32 v113, v193, v99
	v_lshl_add_u64 v[96:97], s[20:21], 0, v[182:183]
	v_lshl_add_u64 v[114:115], v[172:173], 1, v[96:97]
	global_store_dwordx4 v[114:115], v[108:111], off
	v_cvt_pk_bf16_f32 v98, v100, v101
	s_waitcnt lgkmcnt(0)
	v_add_f32_e32 v96, v99, v113
	ds_bpermute_b32 v97, v112, v96
	v_cvt_pk_bf16_f32 v99, v102, v103
	v_cvt_pk_bf16_f32 v100, v106, v107
	v_cvt_pk_bf16_f32 v101, v104, v105
	global_store_dwordx4 v[114:115], v[98:101], off offset:256
	s_and_saveexec_b64 s[58:59], s[8:9]
	s_cbranch_execz .LBB0_447
	s_waitcnt lgkmcnt(0)
	v_add_f32_e32 v96, v96, v97
	ds_write_b32 v188, v96 offset:256
.LBB0_447:
	s_or_b64 exec, exec, s[58:59]
	s_waitcnt vmcnt(7)
	v_lshlrev_b32_e32 v98, 16, v141
	v_and_b32_e32 v99, 0xffff0000, v141
	v_lshlrev_b32_e32 v96, 16, v140
	s_waitcnt lgkmcnt(0)
	v_and_b32_e32 v97, 0xffff0000, v140
	v_pk_add_f32 v[94:95], v[94:95], v[98:99]
	v_pk_add_f32 v[96:97], v[92:93], v[96:97]
	v_pk_mul_f32 v[98:99], v[94:95], v[94:95]
	v_cvt_pk_bf16_f32 v92, v96, v97
	v_cvt_pk_bf16_f32 v93, v94, v95
	v_lshlrev_b32_e32 v94, 16, v142
	v_and_b32_e32 v95, 0xffff0000, v142
	v_pk_fma_f32 v[96:97], v[96:97], v[96:97], v[98:99]
	v_pk_add_f32 v[88:89], v[88:89], v[94:95]
	s_nop 0
	v_pk_fma_f32 v[96:97], v[88:89], v[88:89], v[96:97]
	v_cvt_pk_bf16_f32 v94, v88, v89
	v_lshlrev_b32_e32 v88, 16, v143
	v_and_b32_e32 v89, 0xffff0000, v143
	v_pk_add_f32 v[88:89], v[90:91], v[88:89]
	s_nop 0
	v_pk_fma_f32 v[90:91], v[88:89], v[88:89], v[96:97]
	v_cvt_pk_bf16_f32 v95, v88, v89
	s_waitcnt vmcnt(6)
	v_lshlrev_b32_e32 v88, 16, v136
	v_and_b32_e32 v89, 0xffff0000, v136
	v_pk_add_f32 v[84:85], v[84:85], v[88:89]
	s_nop 0
	v_pk_fma_f32 v[88:89], v[84:85], v[84:85], v[90:91]
	v_lshlrev_b32_e32 v90, 16, v137
	v_and_b32_e32 v91, 0xffff0000, v137
	v_pk_add_f32 v[86:87], v[86:87], v[90:91]
	v_lshlrev_b32_e32 v90, 16, v138
	v_and_b32_e32 v91, 0xffff0000, v138
	v_pk_fma_f32 v[88:89], v[86:87], v[86:87], v[88:89]
	v_pk_add_f32 v[90:91], v[80:81], v[90:91]
	s_nop 0
	v_pk_fma_f32 v[80:81], v[90:91], v[90:91], v[88:89]
	v_lshlrev_b32_e32 v88, 16, v139
	v_and_b32_e32 v89, 0xffff0000, v139
	v_pk_add_f32 v[88:89], v[82:83], v[88:89]
	s_nop 0
	v_pk_fma_f32 v[80:81], v[88:89], v[88:89], v[80:81]
	s_nop 0
	v_add_f32_e32 v83, v80, v81
	ds_bpermute_b32 v98, v193, v83
	v_lshl_add_u64 v[80:81], s[20:21], 0, v[180:181]
	v_lshl_add_u64 v[96:97], v[172:173], 1, v[80:81]
	global_store_dwordx4 v[96:97], v[92:95], off
	v_cvt_pk_bf16_f32 v82, v84, v85
	s_waitcnt lgkmcnt(0)
	v_add_f32_e32 v80, v83, v98
	ds_bpermute_b32 v81, v112, v80
	v_cvt_pk_bf16_f32 v83, v86, v87
	v_cvt_pk_bf16_f32 v84, v90, v91
	v_cvt_pk_bf16_f32 v85, v88, v89
	global_store_dwordx4 v[96:97], v[82:85], off offset:256
	s_and_saveexec_b64 s[58:59], s[8:9]
	s_cbranch_execz .LBB0_449
	s_waitcnt lgkmcnt(0)
	v_add_f32_e32 v80, v80, v81
	ds_write_b32 v188, v80 offset:512
.LBB0_449:
	s_or_b64 exec, exec, s[58:59]
	s_waitcnt vmcnt(7)
	v_lshlrev_b32_e32 v82, 16, v133
	v_and_b32_e32 v83, 0xffff0000, v133
	v_lshlrev_b32_e32 v80, 16, v132
	s_waitcnt lgkmcnt(0)
	v_and_b32_e32 v81, 0xffff0000, v132
	v_pk_add_f32 v[78:79], v[78:79], v[82:83]
	v_pk_add_f32 v[80:81], v[76:77], v[80:81]
	v_pk_mul_f32 v[82:83], v[78:79], v[78:79]
	v_cvt_pk_bf16_f32 v76, v80, v81
	v_cvt_pk_bf16_f32 v77, v78, v79
	v_lshlrev_b32_e32 v78, 16, v134
	v_and_b32_e32 v79, 0xffff0000, v134
	v_pk_fma_f32 v[80:81], v[80:81], v[80:81], v[82:83]
	v_pk_add_f32 v[72:73], v[72:73], v[78:79]
	s_nop 0
	v_pk_fma_f32 v[80:81], v[72:73], v[72:73], v[80:81]
	v_cvt_pk_bf16_f32 v78, v72, v73
	v_lshlrev_b32_e32 v72, 16, v135
	v_and_b32_e32 v73, 0xffff0000, v135
	v_pk_add_f32 v[72:73], v[74:75], v[72:73]
	s_nop 0
	v_pk_fma_f32 v[74:75], v[72:73], v[72:73], v[80:81]
	v_cvt_pk_bf16_f32 v79, v72, v73
	s_waitcnt vmcnt(6)
	v_lshlrev_b32_e32 v72, 16, v128
	v_and_b32_e32 v73, 0xffff0000, v128
	v_pk_add_f32 v[68:69], v[68:69], v[72:73]
	s_nop 0
	v_pk_fma_f32 v[72:73], v[68:69], v[68:69], v[74:75]
	v_lshlrev_b32_e32 v74, 16, v129
	v_and_b32_e32 v75, 0xffff0000, v129
	v_pk_add_f32 v[70:71], v[70:71], v[74:75]
	v_lshlrev_b32_e32 v74, 16, v130
	v_and_b32_e32 v75, 0xffff0000, v130
	v_pk_fma_f32 v[72:73], v[70:71], v[70:71], v[72:73]
	v_pk_add_f32 v[74:75], v[64:65], v[74:75]
	s_nop 0
	v_pk_fma_f32 v[64:65], v[74:75], v[74:75], v[72:73]
	v_lshlrev_b32_e32 v72, 16, v131
	v_and_b32_e32 v73, 0xffff0000, v131
	v_pk_add_f32 v[72:73], v[66:67], v[72:73]
	s_nop 0
	v_pk_fma_f32 v[64:65], v[72:73], v[72:73], v[64:65]
	s_nop 0
	v_add_f32_e32 v67, v64, v65
	ds_bpermute_b32 v82, v193, v67
	v_lshl_add_u64 v[64:65], s[20:21], 0, v[178:179]
	v_lshl_add_u64 v[80:81], v[172:173], 1, v[64:65]
	global_store_dwordx4 v[80:81], v[76:79], off
	v_cvt_pk_bf16_f32 v66, v68, v69
	s_waitcnt lgkmcnt(0)
	v_add_f32_e32 v64, v67, v82
	ds_bpermute_b32 v65, v112, v64
	v_cvt_pk_bf16_f32 v67, v70, v71
	v_cvt_pk_bf16_f32 v68, v74, v75
	v_cvt_pk_bf16_f32 v69, v72, v73
	global_store_dwordx4 v[80:81], v[66:69], off offset:256
	s_and_saveexec_b64 s[58:59], s[8:9]
	s_cbranch_execz .LBB0_451
	s_waitcnt lgkmcnt(0)
	v_add_f32_e32 v64, v64, v65
	ds_write_b32 v188, v64 offset:768

.LBB0_613:
	s_lshl_b32 s21, s21, 8
	v_lshl_or_b32 v172, s20, 8, v187
	v_add_u32_e32 v176, s21, v185
	v_ashrrev_i32_e32 v173, 31, v172
	v_lshlrev_b64 v[202:203], 1, v[172:173]
	v_ashrrev_i32_e32 v177, 31, v176
	v_lshl_add_u64 v[174:175], s[24:25], 0, v[202:203]
	v_lshlrev_b64 v[204:205], 11, v[176:177]
	v_lshl_add_u64 v[128:129], v[174:175], 0, v[204:205]
	global_load_dwordx4 v[194:197], v[128:129], off
	global_load_dwordx4 v[198:201], v[128:129], off offset:256
	v_or_b32_e32 v128, 16, v176
	v_or_b32_e32 v130, 32, v176
	v_or_b32_e32 v132, 48, v176
	v_ashrrev_i32_e32 v129, 31, v128
	v_ashrrev_i32_e32 v131, 31, v130
	v_ashrrev_i32_e32 v133, 31, v132
	v_lshlrev_b64 v[182:183], 11, v[128:129]
	v_lshlrev_b64 v[180:181], 11, v[130:131]
	v_lshlrev_b64 v[178:179], 11, v[132:133]
	v_lshl_add_u64 v[128:129], v[174:175], 0, v[182:183]
	v_lshl_add_u64 v[130:131], v[174:175], 0, v[180:181]
	v_lshl_add_u64 v[206:207], v[174:175], 0, v[178:179]
	global_load_dwordx4 v[148:151], v[128:129], off
	global_load_dwordx4 v[144:147], v[128:129], off offset:256
	global_load_dwordx4 v[140:143], v[130:131], off
	global_load_dwordx4 v[136:139], v[130:131], off offset:256
	global_load_dwordx4 v[132:135], v[206:207], off
	s_nop 0
	global_load_dwordx4 v[128:131], v[206:207], off offset:256
	v_and_b32_e32 v206, 64, v159
	v_xor_b32_e32 v193, 16, v159
	v_add_u32_e32 v206, 64, v206
	v_xor_b32_e32 v207, 32, v159
	v_cmp_lt_i32_e32 vcc, v193, v206
	v_lshl_add_u64 v[204:205], s[24:25], 0, v[204:205]
	v_lshl_add_u64 v[202:203], v[204:205], 0, v[202:203]
	v_cndmask_b32_e32 v193, v159, v193, vcc
	v_cmp_lt_i32_e32 vcc, v207, v206
	v_lshlrev_b32_e32 v193, 2, v193
	s_waitcnt vmcnt(7)
	v_lshlrev_b32_e32 v204, 16, v194
	v_and_b32_e32 v205, 0xffff0000, v194
	v_lshlrev_b32_e32 v194, 16, v195
	v_and_b32_e32 v195, 0xffff0000, v195
	v_cndmask_b32_e32 v212, v159, v207, vcc
	v_lshlrev_b32_e32 v206, 16, v196
	v_and_b32_e32 v207, 0xffff0000, v196
	v_lshlrev_b32_e32 v196, 16, v197
	v_and_b32_e32 v197, 0xffff0000, v197
	s_waitcnt vmcnt(6)
	v_lshlrev_b32_e32 v210, 16, v200
	v_and_b32_e32 v211, 0xffff0000, v200
	v_lshlrev_b32_e32 v200, 16, v201
	v_and_b32_e32 v201, 0xffff0000, v201
	v_pk_fma_f32 v[126:127], v[126:127], 0.5, v[194:195] op_sel_hi:[1,0,1]
	v_pk_fma_f32 v[124:125], v[124:125], 0.5, v[204:205] op_sel_hi:[1,0,1]
	v_pk_fma_f32 v[122:123], v[122:123], 0.5, v[196:197] op_sel_hi:[1,0,1]
	v_pk_fma_f32 v[196:197], v[114:115], 0.5, v[200:201] op_sel_hi:[1,0,1]
	v_pk_mul_f32 v[114:115], v[126:127], v[126:127]
	v_pk_fma_f32 v[120:121], v[120:121], 0.5, v[206:207] op_sel_hi:[1,0,1]
	v_pk_fma_f32 v[114:115], v[124:125], v[124:125], v[114:115]
	v_lshlrev_b32_e32 v208, 16, v198
	v_and_b32_e32 v209, 0xffff0000, v198
	v_pk_fma_f32 v[114:115], v[120:121], v[120:121], v[114:115]
	v_lshlrev_b32_e32 v198, 16, v199
	v_and_b32_e32 v199, 0xffff0000, v199
	v_pk_fma_f32 v[116:117], v[116:117], 0.5, v[208:209] op_sel_hi:[1,0,1]
	v_pk_fma_f32 v[114:115], v[122:123], v[122:123], v[114:115]
	v_pk_fma_f32 v[118:119], v[118:119], 0.5, v[198:199] op_sel_hi:[1,0,1]
	v_pk_fma_f32 v[114:115], v[116:117], v[116:117], v[114:115]
	v_pk_fma_f32 v[194:195], v[112:113], 0.5, v[210:211] op_sel_hi:[1,0,1]
	v_pk_fma_f32 v[114:115], v[118:119], v[118:119], v[114:115]
	v_cvt_pk_bf16_f32 v112, v124, v125
	v_cvt_pk_bf16_f32 v113, v126, v127
	s_nop 0
	v_pk_fma_f32 v[114:115], v[194:195], v[194:195], v[114:115]
	s_nop 0
	v_pk_fma_f32 v[114:115], v[196:197], v[196:197], v[114:115]
	s_nop 0
	v_add_f32_e32 v124, v114, v115
	ds_bpermute_b32 v125, v193, v124
	v_cvt_pk_bf16_f32 v114, v120, v121
	v_cvt_pk_bf16_f32 v115, v122, v123
	global_store_dwordx4 v[202:203], v[112:115], off
	v_cvt_pk_bf16_f32 v116, v116, v117
	v_cvt_pk_bf16_f32 v117, v118, v119
	v_cvt_pk_bf16_f32 v118, v194, v195
	v_cvt_pk_bf16_f32 v119, v196, v197
	global_store_dwordx4 v[202:203], v[116:119], off offset:256
	s_waitcnt lgkmcnt(0)
	v_add_f32_e32 v113, v124, v125
	v_lshlrev_b32_e32 v112, 2, v212
	ds_bpermute_b32 v114, v112, v113
	s_and_saveexec_b64 s[54:55], s[10:11]
	s_cbranch_execz .LBB0_615
	s_waitcnt lgkmcnt(0)
	v_add_f32_e32 v113, v113, v114
	ds_write_b32 v188, v113
.LBB0_615:
	s_or_b64 exec, exec, s[54:55]
	s_waitcnt vmcnt(7)
	v_lshlrev_b32_e32 v116, 16, v149
	v_and_b32_e32 v117, 0xffff0000, v149
	s_waitcnt lgkmcnt(0)
	v_lshlrev_b32_e32 v114, 16, v148
	v_and_b32_e32 v115, 0xffff0000, v148
	v_pk_fma_f32 v[110:111], v[110:111], 0.5, v[116:117] op_sel_hi:[1,0,1]
	v_pk_fma_f32 v[114:115], v[108:109], 0.5, v[114:115] op_sel_hi:[1,0,1]
	v_pk_mul_f32 v[116:117], v[110:111], v[110:111]
	v_cvt_pk_bf16_f32 v108, v114, v115
	v_cvt_pk_bf16_f32 v109, v110, v111
	v_lshlrev_b32_e32 v110, 16, v150
	v_and_b32_e32 v111, 0xffff0000, v150
	v_pk_fma_f32 v[114:115], v[114:115], v[114:115], v[116:117]
	v_pk_fma_f32 v[104:105], v[104:105], 0.5, v[110:111] op_sel_hi:[1,0,1]
	s_nop 0
	v_pk_fma_f32 v[114:115], v[104:105], v[104:105], v[114:115]
	v_cvt_pk_bf16_f32 v110, v104, v105
	v_lshlrev_b32_e32 v104, 16, v151
	v_and_b32_e32 v105, 0xffff0000, v151
	v_pk_fma_f32 v[104:105], v[106:107], 0.5, v[104:105] op_sel_hi:[1,0,1]
	s_nop 0
	v_pk_fma_f32 v[106:107], v[104:105], v[104:105], v[114:115]
	v_cvt_pk_bf16_f32 v111, v104, v105
	s_waitcnt vmcnt(6)
	v_lshlrev_b32_e32 v104, 16, v144
	v_and_b32_e32 v105, 0xffff0000, v144
	v_pk_fma_f32 v[100:101], v[100:101], 0.5, v[104:105] op_sel_hi:[1,0,1]
	s_nop 0
	v_pk_fma_f32 v[104:105], v[100:101], v[100:101], v[106:107]
	v_lshlrev_b32_e32 v106, 16, v145
	v_and_b32_e32 v107, 0xffff0000, v145
	v_pk_fma_f32 v[102:103], v[102:103], 0.5, v[106:107] op_sel_hi:[1,0,1]
	v_lshlrev_b32_e32 v106, 16, v146
	v_and_b32_e32 v107, 0xffff0000, v146
	v_pk_fma_f32 v[104:105], v[102:103], v[102:103], v[104:105]
	v_pk_fma_f32 v[106:107], v[96:97], 0.5, v[106:107] op_sel_hi:[1,0,1]
	s_nop 0
	v_pk_fma_f32 v[96:97], v[106:107], v[106:107], v[104:105]
	v_lshlrev_b32_e32 v104, 16, v147
	v_and_b32_e32 v105, 0xffff0000, v147
	v_pk_fma_f32 v[104:105], v[98:99], 0.5, v[104:105] op_sel_hi:[1,0,1]
	s_nop 0
	v_pk_fma_f32 v[96:97], v[104:105], v[104:105], v[96:97]
	s_nop 0
	v_add_f32_e32 v99, v96, v97
	ds_bpermute_b32 v113, v193, v99
	v_lshl_add_u64 v[96:97], s[24:25], 0, v[182:183]
	v_lshl_add_u64 v[114:115], v[172:173], 1, v[96:97]
	global_store_dwordx4 v[114:115], v[108:111], off
	v_cvt_pk_bf16_f32 v98, v100, v101
	s_waitcnt lgkmcnt(0)
	v_add_f32_e32 v96, v99, v113
	ds_bpermute_b32 v97, v112, v96
	v_cvt_pk_bf16_f32 v99, v102, v103
	v_cvt_pk_bf16_f32 v100, v106, v107
	v_cvt_pk_bf16_f32 v101, v104, v105
	global_store_dwordx4 v[114:115], v[98:101], off offset:256
	s_and_saveexec_b64 s[54:55], s[10:11]
	s_cbranch_execz .LBB0_617
	s_waitcnt lgkmcnt(0)
	v_add_f32_e32 v96, v96, v97
	ds_write_b32 v188, v96 offset:256
.LBB0_617:
	s_or_b64 exec, exec, s[54:55]
	s_waitcnt vmcnt(7)
	v_lshlrev_b32_e32 v98, 16, v141
	v_and_b32_e32 v99, 0xffff0000, v141
	v_lshlrev_b32_e32 v96, 16, v140
	s_waitcnt lgkmcnt(0)
	v_and_b32_e32 v97, 0xffff0000, v140
	v_pk_fma_f32 v[94:95], v[94:95], 0.5, v[98:99] op_sel_hi:[1,0,1]
	v_pk_fma_f32 v[96:97], v[92:93], 0.5, v[96:97] op_sel_hi:[1,0,1]
	v_pk_mul_f32 v[98:99], v[94:95], v[94:95]
	v_cvt_pk_bf16_f32 v92, v96, v97
	v_cvt_pk_bf16_f32 v93, v94, v95
	v_lshlrev_b32_e32 v94, 16, v142
	v_and_b32_e32 v95, 0xffff0000, v142
	v_pk_fma_f32 v[96:97], v[96:97], v[96:97], v[98:99]
	v_pk_fma_f32 v[88:89], v[88:89], 0.5, v[94:95] op_sel_hi:[1,0,1]
	s_nop 0
	v_pk_fma_f32 v[96:97], v[88:89], v[88:89], v[96:97]
	v_cvt_pk_bf16_f32 v94, v88, v89
	v_lshlrev_b32_e32 v88, 16, v143
	v_and_b32_e32 v89, 0xffff0000, v143
	v_pk_fma_f32 v[88:89], v[90:91], 0.5, v[88:89] op_sel_hi:[1,0,1]
	s_nop 0
	v_pk_fma_f32 v[90:91], v[88:89], v[88:89], v[96:97]
	v_cvt_pk_bf16_f32 v95, v88, v89
	s_waitcnt vmcnt(6)
	v_lshlrev_b32_e32 v88, 16, v136
	v_and_b32_e32 v89, 0xffff0000, v136
	v_pk_fma_f32 v[84:85], v[84:85], 0.5, v[88:89] op_sel_hi:[1,0,1]
	s_nop 0
	v_pk_fma_f32 v[88:89], v[84:85], v[84:85], v[90:91]
	v_lshlrev_b32_e32 v90, 16, v137
	v_and_b32_e32 v91, 0xffff0000, v137
	v_pk_fma_f32 v[86:87], v[86:87], 0.5, v[90:91] op_sel_hi:[1,0,1]
	v_lshlrev_b32_e32 v90, 16, v138
	v_and_b32_e32 v91, 0xffff0000, v138
	v_pk_fma_f32 v[88:89], v[86:87], v[86:87], v[88:89]
	v_pk_fma_f32 v[90:91], v[80:81], 0.5, v[90:91] op_sel_hi:[1,0,1]
	s_nop 0
	v_pk_fma_f32 v[80:81], v[90:91], v[90:91], v[88:89]
	v_lshlrev_b32_e32 v88, 16, v139
	v_and_b32_e32 v89, 0xffff0000, v139
	v_pk_fma_f32 v[88:89], v[82:83], 0.5, v[88:89] op_sel_hi:[1,0,1]
	s_nop 0
	v_pk_fma_f32 v[80:81], v[88:89], v[88:89], v[80:81]
	s_nop 0
	v_add_f32_e32 v83, v80, v81
	ds_bpermute_b32 v98, v193, v83
	v_lshl_add_u64 v[80:81], s[24:25], 0, v[180:181]
	v_lshl_add_u64 v[96:97], v[172:173], 1, v[80:81]
	global_store_dwordx4 v[96:97], v[92:95], off
	v_cvt_pk_bf16_f32 v82, v84, v85
	s_waitcnt lgkmcnt(0)
	v_add_f32_e32 v80, v83, v98
	ds_bpermute_b32 v81, v112, v80
	v_cvt_pk_bf16_f32 v83, v86, v87
	v_cvt_pk_bf16_f32 v84, v90, v91
	v_cvt_pk_bf16_f32 v85, v88, v89
	global_store_dwordx4 v[96:97], v[82:85], off offset:256
	s_and_saveexec_b64 s[54:55], s[10:11]
	s_cbranch_execz .LBB0_619
	s_waitcnt lgkmcnt(0)
	v_add_f32_e32 v80, v80, v81
	ds_write_b32 v188, v80 offset:512
.LBB0_619:
	s_or_b64 exec, exec, s[54:55]
	s_waitcnt vmcnt(7)
	v_lshlrev_b32_e32 v82, 16, v133
	v_and_b32_e32 v83, 0xffff0000, v133
	v_lshlrev_b32_e32 v80, 16, v132
	s_waitcnt lgkmcnt(0)
	v_and_b32_e32 v81, 0xffff0000, v132
	v_pk_fma_f32 v[78:79], v[78:79], 0.5, v[82:83] op_sel_hi:[1,0,1]
	v_pk_fma_f32 v[80:81], v[76:77], 0.5, v[80:81] op_sel_hi:[1,0,1]
	v_pk_mul_f32 v[82:83], v[78:79], v[78:79]
	v_cvt_pk_bf16_f32 v76, v80, v81
	v_cvt_pk_bf16_f32 v77, v78, v79
	v_lshlrev_b32_e32 v78, 16, v134
	v_and_b32_e32 v79, 0xffff0000, v134
	v_pk_fma_f32 v[80:81], v[80:81], v[80:81], v[82:83]
	v_pk_fma_f32 v[72:73], v[72:73], 0.5, v[78:79] op_sel_hi:[1,0,1]
	s_nop 0
	v_pk_fma_f32 v[80:81], v[72:73], v[72:73], v[80:81]
	v_cvt_pk_bf16_f32 v78, v72, v73
	v_lshlrev_b32_e32 v72, 16, v135
	v_and_b32_e32 v73, 0xffff0000, v135
	v_pk_fma_f32 v[72:73], v[74:75], 0.5, v[72:73] op_sel_hi:[1,0,1]
	s_nop 0
	v_pk_fma_f32 v[74:75], v[72:73], v[72:73], v[80:81]
	v_cvt_pk_bf16_f32 v79, v72, v73
	s_waitcnt vmcnt(6)
	v_lshlrev_b32_e32 v72, 16, v128
	v_and_b32_e32 v73, 0xffff0000, v128
	v_pk_fma_f32 v[68:69], v[68:69], 0.5, v[72:73] op_sel_hi:[1,0,1]
	s_nop 0
	v_pk_fma_f32 v[72:73], v[68:69], v[68:69], v[74:75]
	v_lshlrev_b32_e32 v74, 16, v129
	v_and_b32_e32 v75, 0xffff0000, v129
	v_pk_fma_f32 v[70:71], v[70:71], 0.5, v[74:75] op_sel_hi:[1,0,1]
	v_lshlrev_b32_e32 v74, 16, v130
	v_and_b32_e32 v75, 0xffff0000, v130
	v_pk_fma_f32 v[72:73], v[70:71], v[70:71], v[72:73]
	v_pk_fma_f32 v[74:75], v[64:65], 0.5, v[74:75] op_sel_hi:[1,0,1]
	s_nop 0
	v_pk_fma_f32 v[64:65], v[74:75], v[74:75], v[72:73]
	v_lshlrev_b32_e32 v72, 16, v131
	v_and_b32_e32 v73, 0xffff0000, v131
	v_pk_fma_f32 v[72:73], v[66:67], 0.5, v[72:73] op_sel_hi:[1,0,1]
	s_nop 0
	v_pk_fma_f32 v[64:65], v[72:73], v[72:73], v[64:65]
	s_nop 0
	v_add_f32_e32 v67, v64, v65
	ds_bpermute_b32 v82, v193, v67
	v_lshl_add_u64 v[64:65], s[24:25], 0, v[178:179]
	v_lshl_add_u64 v[80:81], v[172:173], 1, v[64:65]
	global_store_dwordx4 v[80:81], v[76:79], off
	v_cvt_pk_bf16_f32 v66, v68, v69
	s_waitcnt lgkmcnt(0)
	v_add_f32_e32 v64, v67, v82
	ds_bpermute_b32 v65, v112, v64
	v_cvt_pk_bf16_f32 v67, v70, v71
	v_cvt_pk_bf16_f32 v68, v74, v75
	v_cvt_pk_bf16_f32 v69, v72, v73
	global_store_dwordx4 v[80:81], v[66:69], off offset:256
	s_and_saveexec_b64 s[54:55], s[10:11]
	s_cbranch_execz .LBB0_621
	s_waitcnt lgkmcnt(0)
	v_add_f32_e32 v64, v64, v65
	ds_write_b32 v188, v64 offset:768

.LBB0_1014:
	s_lshl_b32 s15, s56, 8
	v_lshl_or_b32 v172, s14, 8, v186
	v_add_u32_e32 v176, s15, v184
	v_ashrrev_i32_e32 v173, 31, v172
	v_lshlrev_b64 v[202:203], 1, v[172:173]
	v_ashrrev_i32_e32 v177, 31, v176
	v_lshl_add_u64 v[174:175], s[22:23], 0, v[202:203]
	v_lshlrev_b64 v[204:205], 11, v[176:177]
	v_lshl_add_u64 v[128:129], v[174:175], 0, v[204:205]
	global_load_dwordx4 v[194:197], v[128:129], off
	global_load_dwordx4 v[198:201], v[128:129], off offset:256
	v_or_b32_e32 v128, 16, v176
	v_or_b32_e32 v130, 32, v176
	v_or_b32_e32 v132, 48, v176
	v_ashrrev_i32_e32 v129, 31, v128
	v_ashrrev_i32_e32 v131, 31, v130
	v_ashrrev_i32_e32 v133, 31, v132
	v_lshlrev_b64 v[182:183], 11, v[128:129]
	v_lshlrev_b64 v[180:181], 11, v[130:131]
	v_lshlrev_b64 v[178:179], 11, v[132:133]
	v_lshl_add_u64 v[128:129], v[174:175], 0, v[182:183]
	v_lshl_add_u64 v[130:131], v[174:175], 0, v[180:181]
	v_lshl_add_u64 v[192:193], v[174:175], 0, v[178:179]
	global_load_dwordx4 v[148:151], v[128:129], off
	global_load_dwordx4 v[144:147], v[128:129], off offset:256
	global_load_dwordx4 v[140:143], v[130:131], off
	global_load_dwordx4 v[136:139], v[130:131], off offset:256
	global_load_dwordx4 v[132:135], v[192:193], off
	s_nop 0
	global_load_dwordx4 v[128:131], v[192:193], off offset:256
	v_and_b32_e32 v193, 64, v159
	v_xor_b32_e32 v192, 16, v159
	v_add_u32_e32 v193, 64, v193
	v_xor_b32_e32 v206, 32, v159
	v_cmp_lt_i32_e32 vcc, v192, v193
	v_lshl_add_u64 v[204:205], s[22:23], 0, v[204:205]
	v_lshl_add_u64 v[202:203], v[204:205], 0, v[202:203]
	v_cndmask_b32_e32 v192, v159, v192, vcc
	v_cmp_lt_i32_e32 vcc, v206, v193
	v_lshlrev_b32_e32 v192, 2, v192
	s_waitcnt vmcnt(7)
	v_lshlrev_b32_e32 v204, 16, v194
	v_and_b32_e32 v205, 0xffff0000, v194
	v_lshlrev_b32_e32 v194, 16, v195
	v_and_b32_e32 v195, 0xffff0000, v195
	v_cndmask_b32_e32 v193, v159, v206, vcc
	v_lshlrev_b32_e32 v206, 16, v196
	v_and_b32_e32 v207, 0xffff0000, v196
	v_lshlrev_b32_e32 v196, 16, v197
	v_and_b32_e32 v197, 0xffff0000, v197
	s_waitcnt vmcnt(6)
	v_lshlrev_b32_e32 v210, 16, v200
	v_and_b32_e32 v211, 0xffff0000, v200
	v_lshlrev_b32_e32 v200, 16, v201
	v_and_b32_e32 v201, 0xffff0000, v201
	v_pk_add_f32 v[126:127], v[126:127], v[194:195]
	v_pk_add_f32 v[124:125], v[124:125], v[204:205]
	v_pk_add_f32 v[122:123], v[122:123], v[196:197]
	v_pk_add_f32 v[196:197], v[114:115], v[200:201]
	v_pk_mul_f32 v[114:115], v[126:127], v[126:127]
	v_pk_add_f32 v[120:121], v[120:121], v[206:207]
	v_pk_fma_f32 v[114:115], v[124:125], v[124:125], v[114:115]
	v_lshlrev_b32_e32 v208, 16, v198
	v_and_b32_e32 v209, 0xffff0000, v198
	v_pk_fma_f32 v[114:115], v[120:121], v[120:121], v[114:115]
	v_lshlrev_b32_e32 v198, 16, v199
	v_and_b32_e32 v199, 0xffff0000, v199
	v_pk_add_f32 v[116:117], v[116:117], v[208:209]
	v_pk_fma_f32 v[114:115], v[122:123], v[122:123], v[114:115]
	v_pk_add_f32 v[118:119], v[118:119], v[198:199]
	v_pk_fma_f32 v[114:115], v[116:117], v[116:117], v[114:115]
	v_pk_add_f32 v[194:195], v[112:113], v[210:211]
	v_pk_fma_f32 v[114:115], v[118:119], v[118:119], v[114:115]
	v_cvt_pk_bf16_f32 v112, v124, v125
	v_cvt_pk_bf16_f32 v113, v126, v127
	s_nop 0
	v_pk_fma_f32 v[114:115], v[194:195], v[194:195], v[114:115]
	s_nop 0
	v_pk_fma_f32 v[114:115], v[196:197], v[196:197], v[114:115]
	s_nop 0
	v_add_f32_e32 v124, v114, v115
	ds_bpermute_b32 v125, v192, v124
	v_cvt_pk_bf16_f32 v114, v120, v121
	v_cvt_pk_bf16_f32 v115, v122, v123
	global_store_dwordx4 v[202:203], v[112:115], off
	v_cvt_pk_bf16_f32 v116, v116, v117
	v_cvt_pk_bf16_f32 v117, v118, v119
	v_cvt_pk_bf16_f32 v118, v194, v195
	v_cvt_pk_bf16_f32 v119, v196, v197
	global_store_dwordx4 v[202:203], v[116:119], off offset:256
	s_waitcnt lgkmcnt(0)
	v_add_f32_e32 v113, v124, v125
	v_lshlrev_b32_e32 v112, 2, v193
	ds_bpermute_b32 v114, v112, v113
	s_and_saveexec_b64 s[56:57], s[6:7]
	s_cbranch_execz .LBB0_1016
	s_waitcnt lgkmcnt(0)
	v_add_f32_e32 v113, v113, v114
	ds_write_b32 v187, v113
.LBB0_1016:
	s_or_b64 exec, exec, s[56:57]
	s_waitcnt vmcnt(7)
	v_lshlrev_b32_e32 v116, 16, v149
	v_and_b32_e32 v117, 0xffff0000, v149
	s_waitcnt lgkmcnt(0)
	v_lshlrev_b32_e32 v114, 16, v148
	v_and_b32_e32 v115, 0xffff0000, v148
	v_pk_add_f32 v[110:111], v[110:111], v[116:117]
	v_pk_add_f32 v[114:115], v[108:109], v[114:115]
	v_pk_mul_f32 v[116:117], v[110:111], v[110:111]
	v_cvt_pk_bf16_f32 v108, v114, v115
	v_cvt_pk_bf16_f32 v109, v110, v111
	v_lshlrev_b32_e32 v110, 16, v150
	v_and_b32_e32 v111, 0xffff0000, v150
	v_pk_fma_f32 v[114:115], v[114:115], v[114:115], v[116:117]
	v_pk_add_f32 v[104:105], v[104:105], v[110:111]
	s_nop 0
	v_pk_fma_f32 v[114:115], v[104:105], v[104:105], v[114:115]
	v_cvt_pk_bf16_f32 v110, v104, v105
	v_lshlrev_b32_e32 v104, 16, v151
	v_and_b32_e32 v105, 0xffff0000, v151
	v_pk_add_f32 v[104:105], v[106:107], v[104:105]
	s_nop 0
	v_pk_fma_f32 v[106:107], v[104:105], v[104:105], v[114:115]
	v_cvt_pk_bf16_f32 v111, v104, v105
	s_waitcnt vmcnt(6)
	v_lshlrev_b32_e32 v104, 16, v144
	v_and_b32_e32 v105, 0xffff0000, v144
	v_pk_add_f32 v[100:101], v[100:101], v[104:105]
	s_nop 0
	v_pk_fma_f32 v[104:105], v[100:101], v[100:101], v[106:107]
	v_lshlrev_b32_e32 v106, 16, v145
	v_and_b32_e32 v107, 0xffff0000, v145
	v_pk_add_f32 v[102:103], v[102:103], v[106:107]
	v_lshlrev_b32_e32 v106, 16, v146
	v_and_b32_e32 v107, 0xffff0000, v146
	v_pk_fma_f32 v[104:105], v[102:103], v[102:103], v[104:105]
	v_pk_add_f32 v[106:107], v[96:97], v[106:107]
	s_nop 0
	v_pk_fma_f32 v[96:97], v[106:107], v[106:107], v[104:105]
	v_lshlrev_b32_e32 v104, 16, v147
	v_and_b32_e32 v105, 0xffff0000, v147
	v_pk_add_f32 v[104:105], v[98:99], v[104:105]
	s_nop 0
	v_pk_fma_f32 v[96:97], v[104:105], v[104:105], v[96:97]
	s_nop 0
	v_add_f32_e32 v99, v96, v97
	ds_bpermute_b32 v113, v192, v99
	v_lshl_add_u64 v[96:97], s[22:23], 0, v[182:183]
	v_lshl_add_u64 v[114:115], v[172:173], 1, v[96:97]
	global_store_dwordx4 v[114:115], v[108:111], off
	v_cvt_pk_bf16_f32 v98, v100, v101
	s_waitcnt lgkmcnt(0)
	v_add_f32_e32 v96, v99, v113
	ds_bpermute_b32 v97, v112, v96
	v_cvt_pk_bf16_f32 v99, v102, v103
	v_cvt_pk_bf16_f32 v100, v106, v107
	v_cvt_pk_bf16_f32 v101, v104, v105
	global_store_dwordx4 v[114:115], v[98:101], off offset:256
	s_and_saveexec_b64 s[56:57], s[6:7]
	s_cbranch_execz .LBB0_1018
	s_waitcnt lgkmcnt(0)
	v_add_f32_e32 v96, v96, v97
	ds_write_b32 v187, v96 offset:256
.LBB0_1018:
	s_or_b64 exec, exec, s[56:57]
	s_waitcnt vmcnt(7)
	v_lshlrev_b32_e32 v98, 16, v141
	v_and_b32_e32 v99, 0xffff0000, v141
	v_lshlrev_b32_e32 v96, 16, v140
	s_waitcnt lgkmcnt(0)
	v_and_b32_e32 v97, 0xffff0000, v140
	v_pk_add_f32 v[94:95], v[94:95], v[98:99]
	v_pk_add_f32 v[96:97], v[92:93], v[96:97]
	v_pk_mul_f32 v[98:99], v[94:95], v[94:95]
	v_cvt_pk_bf16_f32 v92, v96, v97
	v_cvt_pk_bf16_f32 v93, v94, v95
	v_lshlrev_b32_e32 v94, 16, v142
	v_and_b32_e32 v95, 0xffff0000, v142
	v_pk_fma_f32 v[96:97], v[96:97], v[96:97], v[98:99]
	v_pk_add_f32 v[88:89], v[88:89], v[94:95]
	s_nop 0
	v_pk_fma_f32 v[96:97], v[88:89], v[88:89], v[96:97]
	v_cvt_pk_bf16_f32 v94, v88, v89
	v_lshlrev_b32_e32 v88, 16, v143
	v_and_b32_e32 v89, 0xffff0000, v143
	v_pk_add_f32 v[88:89], v[90:91], v[88:89]
	s_nop 0
	v_pk_fma_f32 v[90:91], v[88:89], v[88:89], v[96:97]
	v_cvt_pk_bf16_f32 v95, v88, v89
	s_waitcnt vmcnt(6)
	v_lshlrev_b32_e32 v88, 16, v136
	v_and_b32_e32 v89, 0xffff0000, v136
	v_pk_add_f32 v[84:85], v[84:85], v[88:89]
	s_nop 0
	v_pk_fma_f32 v[88:89], v[84:85], v[84:85], v[90:91]
	v_lshlrev_b32_e32 v90, 16, v137
	v_and_b32_e32 v91, 0xffff0000, v137
	v_pk_add_f32 v[86:87], v[86:87], v[90:91]
	v_lshlrev_b32_e32 v90, 16, v138
	v_and_b32_e32 v91, 0xffff0000, v138
	v_pk_fma_f32 v[88:89], v[86:87], v[86:87], v[88:89]
	v_pk_add_f32 v[90:91], v[80:81], v[90:91]
	s_nop 0
	v_pk_fma_f32 v[80:81], v[90:91], v[90:91], v[88:89]
	v_lshlrev_b32_e32 v88, 16, v139
	v_and_b32_e32 v89, 0xffff0000, v139
	v_pk_add_f32 v[88:89], v[82:83], v[88:89]
	s_nop 0
	v_pk_fma_f32 v[80:81], v[88:89], v[88:89], v[80:81]
	s_nop 0
	v_add_f32_e32 v83, v80, v81
	ds_bpermute_b32 v98, v192, v83
	v_lshl_add_u64 v[80:81], s[22:23], 0, v[180:181]
	v_lshl_add_u64 v[96:97], v[172:173], 1, v[80:81]
	global_store_dwordx4 v[96:97], v[92:95], off
	v_cvt_pk_bf16_f32 v82, v84, v85
	s_waitcnt lgkmcnt(0)
	v_add_f32_e32 v80, v83, v98
	ds_bpermute_b32 v81, v112, v80
	v_cvt_pk_bf16_f32 v83, v86, v87
	v_cvt_pk_bf16_f32 v84, v90, v91
	v_cvt_pk_bf16_f32 v85, v88, v89
	global_store_dwordx4 v[96:97], v[82:85], off offset:256
	s_and_saveexec_b64 s[56:57], s[6:7]
	s_cbranch_execz .LBB0_1020
	s_waitcnt lgkmcnt(0)
	v_add_f32_e32 v80, v80, v81
	ds_write_b32 v187, v80 offset:512
.LBB0_1020:
	s_or_b64 exec, exec, s[56:57]
	s_waitcnt vmcnt(7)
	v_lshlrev_b32_e32 v82, 16, v133
	v_and_b32_e32 v83, 0xffff0000, v133
	v_lshlrev_b32_e32 v80, 16, v132
	s_waitcnt lgkmcnt(0)
	v_and_b32_e32 v81, 0xffff0000, v132
	v_pk_add_f32 v[78:79], v[78:79], v[82:83]
	v_pk_add_f32 v[80:81], v[76:77], v[80:81]
	v_pk_mul_f32 v[82:83], v[78:79], v[78:79]
	v_cvt_pk_bf16_f32 v76, v80, v81
	v_cvt_pk_bf16_f32 v77, v78, v79
	v_lshlrev_b32_e32 v78, 16, v134
	v_and_b32_e32 v79, 0xffff0000, v134
	v_pk_fma_f32 v[80:81], v[80:81], v[80:81], v[82:83]
	v_pk_add_f32 v[72:73], v[72:73], v[78:79]
	s_nop 0
	v_pk_fma_f32 v[80:81], v[72:73], v[72:73], v[80:81]
	v_cvt_pk_bf16_f32 v78, v72, v73
	v_lshlrev_b32_e32 v72, 16, v135
	v_and_b32_e32 v73, 0xffff0000, v135
	v_pk_add_f32 v[72:73], v[74:75], v[72:73]
	s_nop 0
	v_pk_fma_f32 v[74:75], v[72:73], v[72:73], v[80:81]
	v_cvt_pk_bf16_f32 v79, v72, v73
	s_waitcnt vmcnt(6)
	v_lshlrev_b32_e32 v72, 16, v128
	v_and_b32_e32 v73, 0xffff0000, v128
	v_pk_add_f32 v[68:69], v[68:69], v[72:73]
	s_nop 0
	v_pk_fma_f32 v[72:73], v[68:69], v[68:69], v[74:75]
	v_lshlrev_b32_e32 v74, 16, v129
	v_and_b32_e32 v75, 0xffff0000, v129
	v_pk_add_f32 v[70:71], v[70:71], v[74:75]
	v_lshlrev_b32_e32 v74, 16, v130
	v_and_b32_e32 v75, 0xffff0000, v130
	v_pk_fma_f32 v[72:73], v[70:71], v[70:71], v[72:73]
	v_pk_add_f32 v[74:75], v[64:65], v[74:75]
	s_nop 0
	v_pk_fma_f32 v[64:65], v[74:75], v[74:75], v[72:73]
	v_lshlrev_b32_e32 v72, 16, v131
	v_and_b32_e32 v73, 0xffff0000, v131
	v_pk_add_f32 v[72:73], v[66:67], v[72:73]
	s_nop 0
	v_pk_fma_f32 v[64:65], v[72:73], v[72:73], v[64:65]
	s_nop 0
	v_add_f32_e32 v67, v64, v65
	ds_bpermute_b32 v82, v192, v67
	v_lshl_add_u64 v[64:65], s[22:23], 0, v[178:179]
	v_lshl_add_u64 v[80:81], v[172:173], 1, v[64:65]
	global_store_dwordx4 v[80:81], v[76:79], off
	v_cvt_pk_bf16_f32 v66, v68, v69
	s_waitcnt lgkmcnt(0)
	v_add_f32_e32 v64, v67, v82
	ds_bpermute_b32 v65, v112, v64
	v_cvt_pk_bf16_f32 v67, v70, v71
	v_cvt_pk_bf16_f32 v68, v74, v75
	v_cvt_pk_bf16_f32 v69, v72, v73
	global_store_dwordx4 v[80:81], v[66:69], off offset:256
	s_and_saveexec_b64 s[56:57], s[6:7]
	s_cbranch_execz .LBB0_1022
	s_waitcnt lgkmcnt(0)
	v_add_f32_e32 v64, v64, v65
	ds_write_b32 v187, v64 offset:768

.LBB0_1184:
	s_lshl_b32 s13, s13, 8
	v_lshl_or_b32 v172, s12, 8, v186
	v_add_u32_e32 v176, s13, v184
	v_ashrrev_i32_e32 v173, 31, v172
	v_lshlrev_b64 v[202:203], 1, v[172:173]
	v_ashrrev_i32_e32 v177, 31, v176
	v_lshl_add_u64 v[174:175], s[16:17], 0, v[202:203]
	v_lshlrev_b64 v[204:205], 11, v[176:177]
	v_lshl_add_u64 v[128:129], v[174:175], 0, v[204:205]
	global_load_dwordx4 v[194:197], v[128:129], off
	global_load_dwordx4 v[198:201], v[128:129], off offset:256
	v_or_b32_e32 v128, 16, v176
	v_or_b32_e32 v130, 32, v176
	v_or_b32_e32 v132, 48, v176
	v_ashrrev_i32_e32 v129, 31, v128
	v_ashrrev_i32_e32 v131, 31, v130
	v_ashrrev_i32_e32 v133, 31, v132
	v_lshlrev_b64 v[182:183], 11, v[128:129]
	v_lshlrev_b64 v[180:181], 11, v[130:131]
	v_lshlrev_b64 v[178:179], 11, v[132:133]
	v_lshl_add_u64 v[128:129], v[174:175], 0, v[182:183]
	v_lshl_add_u64 v[130:131], v[174:175], 0, v[180:181]
	v_lshl_add_u64 v[192:193], v[174:175], 0, v[178:179]
	global_load_dwordx4 v[148:151], v[128:129], off
	global_load_dwordx4 v[144:147], v[128:129], off offset:256
	global_load_dwordx4 v[140:143], v[130:131], off
	global_load_dwordx4 v[136:139], v[130:131], off offset:256
	global_load_dwordx4 v[132:135], v[192:193], off
	s_nop 0
	global_load_dwordx4 v[128:131], v[192:193], off offset:256
	v_and_b32_e32 v193, 64, v159
	v_xor_b32_e32 v192, 16, v159
	v_add_u32_e32 v193, 64, v193
	v_xor_b32_e32 v206, 32, v159
	v_cmp_lt_i32_e32 vcc, v192, v193
	v_lshl_add_u64 v[204:205], s[16:17], 0, v[204:205]
	v_lshl_add_u64 v[202:203], v[204:205], 0, v[202:203]
	v_cndmask_b32_e32 v192, v159, v192, vcc
	v_cmp_lt_i32_e32 vcc, v206, v193
	v_lshlrev_b32_e32 v192, 2, v192
	s_waitcnt vmcnt(7)
	v_lshlrev_b32_e32 v204, 16, v194
	v_and_b32_e32 v205, 0xffff0000, v194
	v_lshlrev_b32_e32 v194, 16, v195
	v_and_b32_e32 v195, 0xffff0000, v195
	v_cndmask_b32_e32 v193, v159, v206, vcc
	v_lshlrev_b32_e32 v206, 16, v196
	v_and_b32_e32 v207, 0xffff0000, v196
	v_lshlrev_b32_e32 v196, 16, v197
	v_and_b32_e32 v197, 0xffff0000, v197
	s_waitcnt vmcnt(6)
	v_lshlrev_b32_e32 v210, 16, v200
	v_and_b32_e32 v211, 0xffff0000, v200
	v_lshlrev_b32_e32 v200, 16, v201
	v_and_b32_e32 v201, 0xffff0000, v201
	v_pk_fma_f32 v[126:127], v[126:127], 0.5, v[194:195] op_sel_hi:[1,0,1]
	v_pk_fma_f32 v[124:125], v[124:125], 0.5, v[204:205] op_sel_hi:[1,0,1]
	v_pk_fma_f32 v[122:123], v[122:123], 0.5, v[196:197] op_sel_hi:[1,0,1]
	v_pk_fma_f32 v[196:197], v[114:115], 0.5, v[200:201] op_sel_hi:[1,0,1]
	v_pk_mul_f32 v[114:115], v[126:127], v[126:127]
	v_pk_fma_f32 v[120:121], v[120:121], 0.5, v[206:207] op_sel_hi:[1,0,1]
	v_pk_fma_f32 v[114:115], v[124:125], v[124:125], v[114:115]
	v_lshlrev_b32_e32 v208, 16, v198
	v_and_b32_e32 v209, 0xffff0000, v198
	v_pk_fma_f32 v[114:115], v[120:121], v[120:121], v[114:115]
	v_lshlrev_b32_e32 v198, 16, v199
	v_and_b32_e32 v199, 0xffff0000, v199
	v_pk_fma_f32 v[116:117], v[116:117], 0.5, v[208:209] op_sel_hi:[1,0,1]
	v_pk_fma_f32 v[114:115], v[122:123], v[122:123], v[114:115]
	v_pk_fma_f32 v[118:119], v[118:119], 0.5, v[198:199] op_sel_hi:[1,0,1]
	v_pk_fma_f32 v[114:115], v[116:117], v[116:117], v[114:115]
	v_pk_fma_f32 v[194:195], v[112:113], 0.5, v[210:211] op_sel_hi:[1,0,1]
	v_pk_fma_f32 v[114:115], v[118:119], v[118:119], v[114:115]
	v_cvt_pk_bf16_f32 v112, v124, v125
	v_cvt_pk_bf16_f32 v113, v126, v127
	s_nop 0
	v_pk_fma_f32 v[114:115], v[194:195], v[194:195], v[114:115]
	s_nop 0
	v_pk_fma_f32 v[114:115], v[196:197], v[196:197], v[114:115]
	s_nop 0
	v_add_f32_e32 v124, v114, v115
	ds_bpermute_b32 v125, v192, v124
	v_cvt_pk_bf16_f32 v114, v120, v121
	v_cvt_pk_bf16_f32 v115, v122, v123
	global_store_dwordx4 v[202:203], v[112:115], off
	v_cvt_pk_bf16_f32 v116, v116, v117
	v_cvt_pk_bf16_f32 v117, v118, v119
	v_cvt_pk_bf16_f32 v118, v194, v195
	v_cvt_pk_bf16_f32 v119, v196, v197
	global_store_dwordx4 v[202:203], v[116:119], off offset:256
	s_waitcnt lgkmcnt(0)
	v_add_f32_e32 v113, v124, v125
	v_lshlrev_b32_e32 v112, 2, v193
	ds_bpermute_b32 v114, v112, v113
	s_and_saveexec_b64 s[48:49], s[4:5]
	s_cbranch_execz .LBB0_1186
	s_waitcnt lgkmcnt(0)
	v_add_f32_e32 v113, v113, v114
	ds_write_b32 v187, v113
.LBB0_1186:
	s_or_b64 exec, exec, s[48:49]
	s_waitcnt vmcnt(7)
	v_lshlrev_b32_e32 v116, 16, v149
	v_and_b32_e32 v117, 0xffff0000, v149
	s_waitcnt lgkmcnt(0)
	v_lshlrev_b32_e32 v114, 16, v148
	v_and_b32_e32 v115, 0xffff0000, v148
	v_pk_fma_f32 v[110:111], v[110:111], 0.5, v[116:117] op_sel_hi:[1,0,1]
	v_pk_fma_f32 v[114:115], v[108:109], 0.5, v[114:115] op_sel_hi:[1,0,1]
	v_pk_mul_f32 v[116:117], v[110:111], v[110:111]
	v_cvt_pk_bf16_f32 v108, v114, v115
	v_cvt_pk_bf16_f32 v109, v110, v111
	v_lshlrev_b32_e32 v110, 16, v150
	v_and_b32_e32 v111, 0xffff0000, v150
	v_pk_fma_f32 v[114:115], v[114:115], v[114:115], v[116:117]
	v_pk_fma_f32 v[104:105], v[104:105], 0.5, v[110:111] op_sel_hi:[1,0,1]
	s_nop 0
	v_pk_fma_f32 v[114:115], v[104:105], v[104:105], v[114:115]
	v_cvt_pk_bf16_f32 v110, v104, v105
	v_lshlrev_b32_e32 v104, 16, v151
	v_and_b32_e32 v105, 0xffff0000, v151
	v_pk_fma_f32 v[104:105], v[106:107], 0.5, v[104:105] op_sel_hi:[1,0,1]
	s_nop 0
	v_pk_fma_f32 v[106:107], v[104:105], v[104:105], v[114:115]
	v_cvt_pk_bf16_f32 v111, v104, v105
	s_waitcnt vmcnt(6)
	v_lshlrev_b32_e32 v104, 16, v144
	v_and_b32_e32 v105, 0xffff0000, v144
	v_pk_fma_f32 v[100:101], v[100:101], 0.5, v[104:105] op_sel_hi:[1,0,1]
	s_nop 0
	v_pk_fma_f32 v[104:105], v[100:101], v[100:101], v[106:107]
	v_lshlrev_b32_e32 v106, 16, v145
	v_and_b32_e32 v107, 0xffff0000, v145
	v_pk_fma_f32 v[102:103], v[102:103], 0.5, v[106:107] op_sel_hi:[1,0,1]
	v_lshlrev_b32_e32 v106, 16, v146
	v_and_b32_e32 v107, 0xffff0000, v146
	v_pk_fma_f32 v[104:105], v[102:103], v[102:103], v[104:105]
	v_pk_fma_f32 v[106:107], v[96:97], 0.5, v[106:107] op_sel_hi:[1,0,1]
	s_nop 0
	v_pk_fma_f32 v[96:97], v[106:107], v[106:107], v[104:105]
	v_lshlrev_b32_e32 v104, 16, v147
	v_and_b32_e32 v105, 0xffff0000, v147
	v_pk_fma_f32 v[104:105], v[98:99], 0.5, v[104:105] op_sel_hi:[1,0,1]
	s_nop 0
	v_pk_fma_f32 v[96:97], v[104:105], v[104:105], v[96:97]
	s_nop 0
	v_add_f32_e32 v99, v96, v97
	ds_bpermute_b32 v113, v192, v99
	v_lshl_add_u64 v[96:97], s[16:17], 0, v[182:183]
	v_lshl_add_u64 v[114:115], v[172:173], 1, v[96:97]
	global_store_dwordx4 v[114:115], v[108:111], off
	v_cvt_pk_bf16_f32 v98, v100, v101
	s_waitcnt lgkmcnt(0)
	v_add_f32_e32 v96, v99, v113
	ds_bpermute_b32 v97, v112, v96
	v_cvt_pk_bf16_f32 v99, v102, v103
	v_cvt_pk_bf16_f32 v100, v106, v107
	v_cvt_pk_bf16_f32 v101, v104, v105
	global_store_dwordx4 v[114:115], v[98:101], off offset:256
	s_and_saveexec_b64 s[48:49], s[4:5]
	s_cbranch_execz .LBB0_1188
	s_waitcnt lgkmcnt(0)
	v_add_f32_e32 v96, v96, v97
	ds_write_b32 v187, v96 offset:256
.LBB0_1188:
	s_or_b64 exec, exec, s[48:49]
	s_waitcnt vmcnt(7)
	v_lshlrev_b32_e32 v98, 16, v141
	v_and_b32_e32 v99, 0xffff0000, v141
	v_lshlrev_b32_e32 v96, 16, v140
	s_waitcnt lgkmcnt(0)
	v_and_b32_e32 v97, 0xffff0000, v140
	v_pk_fma_f32 v[94:95], v[94:95], 0.5, v[98:99] op_sel_hi:[1,0,1]
	v_pk_fma_f32 v[96:97], v[92:93], 0.5, v[96:97] op_sel_hi:[1,0,1]
	v_pk_mul_f32 v[98:99], v[94:95], v[94:95]
	v_cvt_pk_bf16_f32 v92, v96, v97
	v_cvt_pk_bf16_f32 v93, v94, v95
	v_lshlrev_b32_e32 v94, 16, v142
	v_and_b32_e32 v95, 0xffff0000, v142
	v_pk_fma_f32 v[96:97], v[96:97], v[96:97], v[98:99]
	v_pk_fma_f32 v[88:89], v[88:89], 0.5, v[94:95] op_sel_hi:[1,0,1]
	s_nop 0
	v_pk_fma_f32 v[96:97], v[88:89], v[88:89], v[96:97]
	v_cvt_pk_bf16_f32 v94, v88, v89
	v_lshlrev_b32_e32 v88, 16, v143
	v_and_b32_e32 v89, 0xffff0000, v143
	v_pk_fma_f32 v[88:89], v[90:91], 0.5, v[88:89] op_sel_hi:[1,0,1]
	s_nop 0
	v_pk_fma_f32 v[90:91], v[88:89], v[88:89], v[96:97]
	v_cvt_pk_bf16_f32 v95, v88, v89
	s_waitcnt vmcnt(6)
	v_lshlrev_b32_e32 v88, 16, v136
	v_and_b32_e32 v89, 0xffff0000, v136
	v_pk_fma_f32 v[84:85], v[84:85], 0.5, v[88:89] op_sel_hi:[1,0,1]
	s_nop 0
	v_pk_fma_f32 v[88:89], v[84:85], v[84:85], v[90:91]
	v_lshlrev_b32_e32 v90, 16, v137
	v_and_b32_e32 v91, 0xffff0000, v137
	v_pk_fma_f32 v[86:87], v[86:87], 0.5, v[90:91] op_sel_hi:[1,0,1]
	v_lshlrev_b32_e32 v90, 16, v138
	v_and_b32_e32 v91, 0xffff0000, v138
	v_pk_fma_f32 v[88:89], v[86:87], v[86:87], v[88:89]
	v_pk_fma_f32 v[90:91], v[80:81], 0.5, v[90:91] op_sel_hi:[1,0,1]
	s_nop 0
	v_pk_fma_f32 v[80:81], v[90:91], v[90:91], v[88:89]
	v_lshlrev_b32_e32 v88, 16, v139
	v_and_b32_e32 v89, 0xffff0000, v139
	v_pk_fma_f32 v[88:89], v[82:83], 0.5, v[88:89] op_sel_hi:[1,0,1]
	s_nop 0
	v_pk_fma_f32 v[80:81], v[88:89], v[88:89], v[80:81]
	s_nop 0
	v_add_f32_e32 v83, v80, v81
	ds_bpermute_b32 v98, v192, v83
	v_lshl_add_u64 v[80:81], s[16:17], 0, v[180:181]
	v_lshl_add_u64 v[96:97], v[172:173], 1, v[80:81]
	global_store_dwordx4 v[96:97], v[92:95], off
	v_cvt_pk_bf16_f32 v82, v84, v85
	s_waitcnt lgkmcnt(0)
	v_add_f32_e32 v80, v83, v98
	ds_bpermute_b32 v81, v112, v80
	v_cvt_pk_bf16_f32 v83, v86, v87
	v_cvt_pk_bf16_f32 v84, v90, v91
	v_cvt_pk_bf16_f32 v85, v88, v89
	global_store_dwordx4 v[96:97], v[82:85], off offset:256
	s_and_saveexec_b64 s[48:49], s[4:5]
	s_cbranch_execz .LBB0_1190
	s_waitcnt lgkmcnt(0)
	v_add_f32_e32 v80, v80, v81
	ds_write_b32 v187, v80 offset:512
.LBB0_1190:
	s_or_b64 exec, exec, s[48:49]
	s_waitcnt vmcnt(7)
	v_lshlrev_b32_e32 v82, 16, v133
	v_and_b32_e32 v83, 0xffff0000, v133
	v_lshlrev_b32_e32 v80, 16, v132
	s_waitcnt lgkmcnt(0)
	v_and_b32_e32 v81, 0xffff0000, v132
	v_pk_fma_f32 v[78:79], v[78:79], 0.5, v[82:83] op_sel_hi:[1,0,1]
	v_pk_fma_f32 v[80:81], v[76:77], 0.5, v[80:81] op_sel_hi:[1,0,1]
	v_pk_mul_f32 v[82:83], v[78:79], v[78:79]
	v_cvt_pk_bf16_f32 v76, v80, v81
	v_cvt_pk_bf16_f32 v77, v78, v79
	v_lshlrev_b32_e32 v78, 16, v134
	v_and_b32_e32 v79, 0xffff0000, v134
	v_pk_fma_f32 v[80:81], v[80:81], v[80:81], v[82:83]
	v_pk_fma_f32 v[72:73], v[72:73], 0.5, v[78:79] op_sel_hi:[1,0,1]
	s_nop 0
	v_pk_fma_f32 v[80:81], v[72:73], v[72:73], v[80:81]
	v_cvt_pk_bf16_f32 v78, v72, v73
	v_lshlrev_b32_e32 v72, 16, v135
	v_and_b32_e32 v73, 0xffff0000, v135
	v_pk_fma_f32 v[72:73], v[74:75], 0.5, v[72:73] op_sel_hi:[1,0,1]
	s_nop 0
	v_pk_fma_f32 v[74:75], v[72:73], v[72:73], v[80:81]
	v_cvt_pk_bf16_f32 v79, v72, v73
	s_waitcnt vmcnt(6)
	v_lshlrev_b32_e32 v72, 16, v128
	v_and_b32_e32 v73, 0xffff0000, v128
	v_pk_fma_f32 v[68:69], v[68:69], 0.5, v[72:73] op_sel_hi:[1,0,1]
	s_nop 0
	v_pk_fma_f32 v[72:73], v[68:69], v[68:69], v[74:75]
	v_lshlrev_b32_e32 v74, 16, v129
	v_and_b32_e32 v75, 0xffff0000, v129
	v_pk_fma_f32 v[70:71], v[70:71], 0.5, v[74:75] op_sel_hi:[1,0,1]
	v_lshlrev_b32_e32 v74, 16, v130
	v_and_b32_e32 v75, 0xffff0000, v130
	v_pk_fma_f32 v[72:73], v[70:71], v[70:71], v[72:73]
	v_pk_fma_f32 v[74:75], v[64:65], 0.5, v[74:75] op_sel_hi:[1,0,1]
	s_nop 0
	v_pk_fma_f32 v[64:65], v[74:75], v[74:75], v[72:73]
	v_lshlrev_b32_e32 v72, 16, v131
	v_and_b32_e32 v73, 0xffff0000, v131
	v_pk_fma_f32 v[72:73], v[66:67], 0.5, v[72:73] op_sel_hi:[1,0,1]
	s_nop 0
	v_pk_fma_f32 v[64:65], v[72:73], v[72:73], v[64:65]
	s_nop 0
	v_add_f32_e32 v67, v64, v65
	ds_bpermute_b32 v82, v192, v67
	v_lshl_add_u64 v[64:65], s[16:17], 0, v[178:179]
	v_lshl_add_u64 v[80:81], v[172:173], 1, v[64:65]
	global_store_dwordx4 v[80:81], v[76:79], off
	v_cvt_pk_bf16_f32 v66, v68, v69
	s_waitcnt lgkmcnt(0)
	v_add_f32_e32 v64, v67, v82
	ds_bpermute_b32 v65, v112, v64
	v_cvt_pk_bf16_f32 v67, v70, v71
	v_cvt_pk_bf16_f32 v68, v74, v75
	v_cvt_pk_bf16_f32 v69, v72, v73
	global_store_dwordx4 v[80:81], v[66:69], off offset:256
	s_and_saveexec_b64 s[48:49], s[4:5]
	s_cbranch_execz .LBB0_1192
	s_waitcnt lgkmcnt(0)
	v_add_f32_e32 v64, v64, v65
	ds_write_b32 v187, v64 offset:768
